# out-proj epilogue: the 16 staged-accumulator LDS reads of a batch issued together behind the x-row loads (counted waits)
# baseline (speedup 1.0000x reference)
; template <int MODE>
; DI void gemm_phase(const Params& p, int layer, int hf, unsigned char* shmc, int tid) {
;     ...
;         {
;           const int r0 = tid >> 6, ch = tid & 63;
;           const int growb = hf * HROWS + brow + ai * HALF;
;           const float* gate = modb + (size_t)(layer * 4 + (growb >> 13)) * 3072 + 2048 + bcol + ch * 4;
;           const float4 g = *(const float4*)gate;
; #pragma unroll 4
;           for (int i = 0; i < 16; ++i) {
;             const int row = r0 + 8 * i;
;             const float4 v = *(const float4*)(shmc + row * 1040 + ch * 16);
;             const size_t off = (size_t)(growb + row) * DM + bcol + ch * 4;
;             const f32x4 xo = __builtin_nontemporal_load((const f32x4*)(xin + off));
;             f32x4 o; o[0] = xo[0] + g.x * v.x; o[1] = xo[1] + g.y * v.y; o[2] = xo[2] + g.z * v.z; o[3] = xo[3] + g.w * v.w;
;             __builtin_nontemporal_store(o, (f32x4*)(p.out + off));
;           }
.LBB0_705:
	v_lshlrev_b32_e32 v74, 10, v72
	v_add_u32_e32 v74, v74, v68
	v_lshlrev_b32_e32 v74, 2, v74
	s_mov_b64 s[98:99], s[6:7]
	global_load_dwordx4 v[76:79], v74, s[98:99] nt
	s_add_u32 s98, s98, 0x8000
	s_addc_u32 s99, s99, 0
	global_load_dwordx4 v[80:83], v74, s[98:99] nt
	s_add_u32 s98, s98, 0x8000
	s_addc_u32 s99, s99, 0
	global_load_dwordx4 v[84:87], v74, s[98:99] nt
	s_add_u32 s98, s98, 0x8000
	s_addc_u32 s99, s99, 0
	global_load_dwordx4 v[88:91], v74, s[98:99] nt
	s_add_u32 s98, s98, 0x8000
	s_addc_u32 s99, s99, 0
	global_load_dwordx4 v[92:95], v74, s[98:99] nt
	s_add_u32 s98, s98, 0x8000
	s_addc_u32 s99, s99, 0
	global_load_dwordx4 v[96:99], v74, s[98:99] nt
	s_add_u32 s98, s98, 0x8000
	s_addc_u32 s99, s99, 0
	global_load_dwordx4 v[100:103], v74, s[98:99] nt
	s_add_u32 s98, s98, 0x8000
	s_addc_u32 s99, s99, 0
	global_load_dwordx4 v[104:107], v74, s[98:99] nt
	s_add_u32 s98, s98, 0x8000
	s_addc_u32 s99, s99, 0
	global_load_dwordx4 v[108:111], v74, s[98:99] nt
	s_add_u32 s98, s98, 0x8000
	s_addc_u32 s99, s99, 0
	global_load_dwordx4 v[112:115], v74, s[98:99] nt
	s_add_u32 s98, s98, 0x8000
	s_addc_u32 s99, s99, 0
	global_load_dwordx4 v[116:119], v74, s[98:99] nt
	s_add_u32 s98, s98, 0x8000
	s_addc_u32 s99, s99, 0
	global_load_dwordx4 v[120:123], v74, s[98:99] nt
	s_add_u32 s98, s98, 0x8000
	s_addc_u32 s99, s99, 0
	global_load_dwordx4 v[124:127], v74, s[98:99] nt
	s_add_u32 s98, s98, 0x8000
	s_addc_u32 s99, s99, 0
	global_load_dwordx4 v[128:131], v74, s[98:99] nt
	s_add_u32 s98, s98, 0x8000
	s_addc_u32 s99, s99, 0
	global_load_dwordx4 v[132:135], v74, s[98:99] nt
	s_add_u32 s98, s98, 0x8000
	s_addc_u32 s99, s99, 0
	global_load_dwordx4 v[136:139], v74, s[98:99] nt
	s_mov_b64 s[98:99], s[36:37]
	ds_read_b128 v[204:207], v73
	ds_read_b128 v[208:211], v73 offset:8320
	ds_read_b128 v[212:215], v73 offset:16640
	ds_read_b128 v[216:219], v73 offset:24960
	v_add_u32_e32 v73, 0x8200, v73
	ds_read_b128 v[220:223], v73
	ds_read_b128 v[224:227], v73 offset:8320
	ds_read_b128 v[228:231], v73 offset:16640
	ds_read_b128 v[232:235], v73 offset:24960
	v_add_u32_e32 v73, 0x8200, v73
	ds_read_b128 v[236:239], v73
	ds_read_b128 v[240:243], v73 offset:8320
	ds_read_b128 v[244:247], v73 offset:16640
	ds_read_b128 v[248:251], v73 offset:24960
	v_add_u32_e32 v73, 0x8200, v73
	ds_read_b128 v[144:147], v73
	ds_read_b128 v[148:151], v73 offset:8320
	ds_read_b128 v[152:155], v73 offset:16640
	ds_read_b128 v[156:159], v73 offset:24960
	s_waitcnt vmcnt(15) lgkmcnt(15)
	v_pk_fma_f32 v[78:79], v[66:67], v[206:207], v[78:79]
	v_pk_fma_f32 v[76:77], v[64:65], v[204:205], v[76:77]
	global_store_dwordx4 v74, v[76:79], s[98:99] nt
	s_add_u32 s98, s98, 0x8000
	s_addc_u32 s99, s99, 0
	s_waitcnt vmcnt(15) lgkmcnt(14)
	v_pk_fma_f32 v[82:83], v[66:67], v[210:211], v[82:83]
	v_pk_fma_f32 v[80:81], v[64:65], v[208:209], v[80:81]
	global_store_dwordx4 v74, v[80:83], s[98:99] nt
	s_add_u32 s98, s98, 0x8000
	s_addc_u32 s99, s99, 0
	s_waitcnt vmcnt(15) lgkmcnt(13)
	v_pk_fma_f32 v[86:87], v[66:67], v[214:215], v[86:87]
	v_pk_fma_f32 v[84:85], v[64:65], v[212:213], v[84:85]
	global_store_dwordx4 v74, v[84:87], s[98:99] nt
	s_add_u32 s98, s98, 0x8000
	s_addc_u32 s99, s99, 0
	s_waitcnt vmcnt(15) lgkmcnt(12)
	v_pk_fma_f32 v[90:91], v[66:67], v[218:219], v[90:91]
	v_pk_fma_f32 v[88:89], v[64:65], v[216:217], v[88:89]
	global_store_dwordx4 v74, v[88:91], s[98:99] nt
	s_add_u32 s98, s98, 0x8000
	s_addc_u32 s99, s99, 0
	s_waitcnt vmcnt(15) lgkmcnt(11)
	v_pk_fma_f32 v[94:95], v[66:67], v[222:223], v[94:95]
	v_pk_fma_f32 v[92:93], v[64:65], v[220:221], v[92:93]
	global_store_dwordx4 v74, v[92:95], s[98:99] nt
	s_add_u32 s98, s98, 0x8000
	s_addc_u32 s99, s99, 0
	s_waitcnt vmcnt(15) lgkmcnt(10)
	v_pk_fma_f32 v[98:99], v[66:67], v[226:227], v[98:99]
	v_pk_fma_f32 v[96:97], v[64:65], v[224:225], v[96:97]
	global_store_dwordx4 v74, v[96:99], s[98:99] nt
	s_add_u32 s98, s98, 0x8000
	s_addc_u32 s99, s99, 0
	s_waitcnt vmcnt(15) lgkmcnt(9)
	v_pk_fma_f32 v[102:103], v[66:67], v[230:231], v[102:103]
	v_pk_fma_f32 v[100:101], v[64:65], v[228:229], v[100:101]
	global_store_dwordx4 v74, v[100:103], s[98:99] nt
	s_add_u32 s98, s98, 0x8000
	s_addc_u32 s99, s99, 0
	s_waitcnt vmcnt(15) lgkmcnt(8)
	v_pk_fma_f32 v[106:107], v[66:67], v[234:235], v[106:107]
	v_pk_fma_f32 v[104:105], v[64:65], v[232:233], v[104:105]
	global_store_dwordx4 v74, v[104:107], s[98:99] nt
	s_add_u32 s98, s98, 0x8000
	s_addc_u32 s99, s99, 0
	s_waitcnt vmcnt(15) lgkmcnt(7)
	v_pk_fma_f32 v[110:111], v[66:67], v[238:239], v[110:111]
	v_pk_fma_f32 v[108:109], v[64:65], v[236:237], v[108:109]
	global_store_dwordx4 v74, v[108:111], s[98:99] nt
	s_add_u32 s98, s98, 0x8000
	s_addc_u32 s99, s99, 0
	s_waitcnt vmcnt(15) lgkmcnt(6)
	v_pk_fma_f32 v[114:115], v[66:67], v[242:243], v[114:115]
	v_pk_fma_f32 v[112:113], v[64:65], v[240:241], v[112:113]
	global_store_dwordx4 v74, v[112:115], s[98:99] nt
	s_add_u32 s98, s98, 0x8000
	s_addc_u32 s99, s99, 0
	s_waitcnt vmcnt(15) lgkmcnt(5)
	v_pk_fma_f32 v[118:119], v[66:67], v[246:247], v[118:119]
	v_pk_fma_f32 v[116:117], v[64:65], v[244:245], v[116:117]
	global_store_dwordx4 v74, v[116:119], s[98:99] nt
	s_add_u32 s98, s98, 0x8000
	s_addc_u32 s99, s99, 0
	s_waitcnt vmcnt(15) lgkmcnt(4)
	v_pk_fma_f32 v[122:123], v[66:67], v[250:251], v[122:123]
	v_pk_fma_f32 v[120:121], v[64:65], v[248:249], v[120:121]
	global_store_dwordx4 v74, v[120:123], s[98:99] nt
	s_add_u32 s98, s98, 0x8000
	s_addc_u32 s99, s99, 0
	s_waitcnt vmcnt(15) lgkmcnt(3)
	v_pk_fma_f32 v[126:127], v[66:67], v[146:147], v[126:127]
	v_pk_fma_f32 v[124:125], v[64:65], v[144:145], v[124:125]
	global_store_dwordx4 v74, v[124:127], s[98:99] nt
	s_add_u32 s98, s98, 0x8000
	s_addc_u32 s99, s99, 0
	s_waitcnt vmcnt(15) lgkmcnt(2)
	v_pk_fma_f32 v[130:131], v[66:67], v[150:151], v[130:131]
	v_pk_fma_f32 v[128:129], v[64:65], v[148:149], v[128:129]
	global_store_dwordx4 v74, v[128:131], s[98:99] nt
	s_add_u32 s98, s98, 0x8000
	s_addc_u32 s99, s99, 0
	s_waitcnt vmcnt(15) lgkmcnt(1)
	v_pk_fma_f32 v[134:135], v[66:67], v[154:155], v[134:135]
	v_pk_fma_f32 v[132:133], v[64:65], v[152:153], v[132:133]
	global_store_dwordx4 v74, v[132:135], s[98:99] nt
	s_add_u32 s98, s98, 0x8000
	s_addc_u32 s99, s99, 0
	s_waitcnt vmcnt(15) lgkmcnt(0)
	v_pk_fma_f32 v[138:139], v[66:67], v[158:159], v[138:139]
	v_pk_fma_f32 v[136:137], v[64:65], v[156:157], v[136:137]
	global_store_dwordx4 v74, v[136:139], s[98:99] nt
	s_barrier
; template <int MODE>
; DI void gemm_phase(const Params& p, int layer, int hf, unsigned char* shmc, int tid) {
;     ...
;       for (int ai = 0; ai < 2; ++ai) {
; #pragma unroll
;         for (int m = 0; m < 4; ++m) {
;           unsigned char* rp = shmc + (wr * 64 + m * 16 + fr) * 1040 + (wc * 32 + fq * 4) * 4;
; #pragma unroll
;           for (int bj = 0; bj < 2; ++bj)
; #pragma unroll
;             for (int n = 0; n < 2; ++n) *(f32x4*)(rp + (bj * HALF + n * 16) * 4) = acc[ai][bj][m][n];
;         }
;         __syncthreads();
;         {
;           const int r0 = tid >> 6, ch = tid & 63;
;           const int growb = hf * HROWS + brow + ai * HALF;
;           const float* gate = modb + (size_t)(layer * 4 + (growb >> 13)) * 3072 + 2048 + bcol + ch * 4;
;           const float4 g = *(const float4*)gate;
	ds_write_b128 v177, v[12:15]
	ds_write_b128 v177, v[8:11] offset:64
	ds_write_b128 v177, v[32:35] offset:512
	ds_write_b128 v177, v[36:39] offset:576
	ds_write_b128 v177, v[4:7] offset:16640
	ds_write_b128 v177, v[0:3] offset:16704
	ds_write_b128 v177, v[40:43] offset:17152
	ds_write_b128 v177, v[44:47] offset:17216
	ds_write_b128 v177, v[16:19] offset:33280
	ds_write_b128 v177, v[20:23] offset:33344
	ds_write_b128 v177, v[48:51] offset:33792
	ds_write_b128 v177, v[52:55] offset:33856
	ds_write_b128 v177, v[24:27] offset:49920
	ds_write_b128 v177, v[28:31] offset:49984
	ds_write_b128 v177, v[56:59] offset:50432
	ds_write_b128 v177, v[60:63] offset:50496
	s_waitcnt lgkmcnt(0)
	s_barrier
	global_load_dwordx4 v[0:3], v[70:71], off
	s_mov_b32 s4, 0
	v_mov_b32_e32 v4, v176
; template <int MODE>
; DI void gemm_phase(const Params& p, int layer, int hf, unsigned char* shmc, int tid) {
;     ...
;         {
;           const int r0 = tid >> 6, ch = tid & 63;
;           const int growb = hf * HROWS + brow + ai * HALF;
;           const float* gate = modb + (size_t)(layer * 4 + (growb >> 13)) * 3072 + 2048 + bcol + ch * 4;
;           const float4 g = *(const float4*)gate;
; #pragma unroll 4
;           for (int i = 0; i < 16; ++i) {
;             const int row = r0 + 8 * i;
;             const float4 v = *(const float4*)(shmc + row * 1040 + ch * 16);
;             const size_t off = (size_t)(growb + row) * DM + bcol + ch * 4;
;             const f32x4 xo = __builtin_nontemporal_load((const f32x4*)(xin + off));
;             f32x4 o; o[0] = xo[0] + g.x * v.x; o[1] = xo[1] + g.y * v.y; o[2] = xo[2] + g.z * v.z; o[3] = xo[3] + g.w * v.w;
;             __builtin_nontemporal_store(o, (f32x4*)(p.out + off));
;           }
;         }
;         __syncthreads();
;       }
;     }
;     u = un; have = have_n;
.LBB0_707:
	v_add_u32_e32 v74, 0x80, v72
	v_lshlrev_b32_e32 v74, 10, v74
	v_add_u32_e32 v74, v74, v68
	v_lshlrev_b32_e32 v74, 2, v74
	s_mov_b64 s[98:99], s[6:7]
	global_load_dwordx4 v[76:79], v74, s[98:99] nt
	s_add_u32 s98, s98, 0x8000
	s_addc_u32 s99, s99, 0
	global_load_dwordx4 v[80:83], v74, s[98:99] nt
	s_add_u32 s98, s98, 0x8000
	s_addc_u32 s99, s99, 0
	global_load_dwordx4 v[84:87], v74, s[98:99] nt
	s_add_u32 s98, s98, 0x8000
	s_addc_u32 s99, s99, 0
	global_load_dwordx4 v[88:91], v74, s[98:99] nt
	s_add_u32 s98, s98, 0x8000
	s_addc_u32 s99, s99, 0
	global_load_dwordx4 v[92:95], v74, s[98:99] nt
	s_add_u32 s98, s98, 0x8000
	s_addc_u32 s99, s99, 0
	global_load_dwordx4 v[96:99], v74, s[98:99] nt
	s_add_u32 s98, s98, 0x8000
	s_addc_u32 s99, s99, 0
	global_load_dwordx4 v[100:103], v74, s[98:99] nt
	s_add_u32 s98, s98, 0x8000
	s_addc_u32 s99, s99, 0
	global_load_dwordx4 v[104:107], v74, s[98:99] nt
	s_add_u32 s98, s98, 0x8000
	s_addc_u32 s99, s99, 0
	global_load_dwordx4 v[108:111], v74, s[98:99] nt
	s_add_u32 s98, s98, 0x8000
	s_addc_u32 s99, s99, 0
	global_load_dwordx4 v[112:115], v74, s[98:99] nt
	s_add_u32 s98, s98, 0x8000
	s_addc_u32 s99, s99, 0
	global_load_dwordx4 v[116:119], v74, s[98:99] nt
	s_add_u32 s98, s98, 0x8000
	s_addc_u32 s99, s99, 0
	global_load_dwordx4 v[120:123], v74, s[98:99] nt
	s_add_u32 s98, s98, 0x8000
	s_addc_u32 s99, s99, 0
	global_load_dwordx4 v[124:127], v74, s[98:99] nt
	s_add_u32 s98, s98, 0x8000
	s_addc_u32 s99, s99, 0
	global_load_dwordx4 v[128:131], v74, s[98:99] nt
	s_add_u32 s98, s98, 0x8000
	s_addc_u32 s99, s99, 0
	global_load_dwordx4 v[132:135], v74, s[98:99] nt
	s_add_u32 s98, s98, 0x8000
	s_addc_u32 s99, s99, 0
	global_load_dwordx4 v[136:139], v74, s[98:99] nt
	s_mov_b64 s[98:99], s[36:37]
	ds_read_b128 v[204:207], v4
	ds_read_b128 v[208:211], v4 offset:8320
	ds_read_b128 v[212:215], v4 offset:16640
	ds_read_b128 v[216:219], v4 offset:24960
	v_add_u32_e32 v4, 0x8200, v4
	ds_read_b128 v[220:223], v4
	ds_read_b128 v[224:227], v4 offset:8320
	ds_read_b128 v[228:231], v4 offset:16640
	ds_read_b128 v[232:235], v4 offset:24960
	v_add_u32_e32 v4, 0x8200, v4
	ds_read_b128 v[236:239], v4
	ds_read_b128 v[240:243], v4 offset:8320
	ds_read_b128 v[244:247], v4 offset:16640
	ds_read_b128 v[248:251], v4 offset:24960
	v_add_u32_e32 v4, 0x8200, v4
	ds_read_b128 v[144:147], v4
	ds_read_b128 v[148:151], v4 offset:8320
	ds_read_b128 v[152:155], v4 offset:16640
	ds_read_b128 v[156:159], v4 offset:24960
	s_waitcnt vmcnt(15) lgkmcnt(15)
	v_pk_fma_f32 v[78:79], v[2:3], v[206:207], v[78:79]
	v_pk_fma_f32 v[76:77], v[0:1], v[204:205], v[76:77]
	global_store_dwordx4 v74, v[76:79], s[98:99] nt
	s_add_u32 s98, s98, 0x8000
	s_addc_u32 s99, s99, 0
	s_waitcnt vmcnt(15) lgkmcnt(14)
	v_pk_fma_f32 v[82:83], v[2:3], v[210:211], v[82:83]
	v_pk_fma_f32 v[80:81], v[0:1], v[208:209], v[80:81]
	global_store_dwordx4 v74, v[80:83], s[98:99] nt
	s_add_u32 s98, s98, 0x8000
	s_addc_u32 s99, s99, 0
	s_waitcnt vmcnt(15) lgkmcnt(13)
	v_pk_fma_f32 v[86:87], v[2:3], v[214:215], v[86:87]
	v_pk_fma_f32 v[84:85], v[0:1], v[212:213], v[84:85]
	global_store_dwordx4 v74, v[84:87], s[98:99] nt
	s_add_u32 s98, s98, 0x8000
	s_addc_u32 s99, s99, 0
	s_waitcnt vmcnt(15) lgkmcnt(12)
	v_pk_fma_f32 v[90:91], v[2:3], v[218:219], v[90:91]
	v_pk_fma_f32 v[88:89], v[0:1], v[216:217], v[88:89]
	global_store_dwordx4 v74, v[88:91], s[98:99] nt
	s_add_u32 s98, s98, 0x8000
	s_addc_u32 s99, s99, 0
	s_waitcnt vmcnt(15) lgkmcnt(11)
	v_pk_fma_f32 v[94:95], v[2:3], v[222:223], v[94:95]
	v_pk_fma_f32 v[92:93], v[0:1], v[220:221], v[92:93]
	global_store_dwordx4 v74, v[92:95], s[98:99] nt
	s_add_u32 s98, s98, 0x8000
	s_addc_u32 s99, s99, 0
	s_waitcnt vmcnt(15) lgkmcnt(10)
	v_pk_fma_f32 v[98:99], v[2:3], v[226:227], v[98:99]
	v_pk_fma_f32 v[96:97], v[0:1], v[224:225], v[96:97]
	global_store_dwordx4 v74, v[96:99], s[98:99] nt
	s_add_u32 s98, s98, 0x8000
	s_addc_u32 s99, s99, 0
	s_waitcnt vmcnt(15) lgkmcnt(9)
	v_pk_fma_f32 v[102:103], v[2:3], v[230:231], v[102:103]
	v_pk_fma_f32 v[100:101], v[0:1], v[228:229], v[100:101]
	global_store_dwordx4 v74, v[100:103], s[98:99] nt
	s_add_u32 s98, s98, 0x8000
	s_addc_u32 s99, s99, 0
	s_waitcnt vmcnt(15) lgkmcnt(8)
	v_pk_fma_f32 v[106:107], v[2:3], v[234:235], v[106:107]
	v_pk_fma_f32 v[104:105], v[0:1], v[232:233], v[104:105]
	global_store_dwordx4 v74, v[104:107], s[98:99] nt
	s_add_u32 s98, s98, 0x8000
	s_addc_u32 s99, s99, 0
	s_waitcnt vmcnt(15) lgkmcnt(7)
	v_pk_fma_f32 v[110:111], v[2:3], v[238:239], v[110:111]
	v_pk_fma_f32 v[108:109], v[0:1], v[236:237], v[108:109]
	global_store_dwordx4 v74, v[108:111], s[98:99] nt
	s_add_u32 s98, s98, 0x8000
	s_addc_u32 s99, s99, 0
	s_waitcnt vmcnt(15) lgkmcnt(6)
	v_pk_fma_f32 v[114:115], v[2:3], v[242:243], v[114:115]
	v_pk_fma_f32 v[112:113], v[0:1], v[240:241], v[112:113]
	global_store_dwordx4 v74, v[112:115], s[98:99] nt
	s_add_u32 s98, s98, 0x8000
	s_addc_u32 s99, s99, 0
	s_waitcnt vmcnt(15) lgkmcnt(5)
	v_pk_fma_f32 v[118:119], v[2:3], v[246:247], v[118:119]
	v_pk_fma_f32 v[116:117], v[0:1], v[244:245], v[116:117]
	global_store_dwordx4 v74, v[116:119], s[98:99] nt
	s_add_u32 s98, s98, 0x8000
	s_addc_u32 s99, s99, 0
	s_waitcnt vmcnt(15) lgkmcnt(4)
	v_pk_fma_f32 v[122:123], v[2:3], v[250:251], v[122:123]
	v_pk_fma_f32 v[120:121], v[0:1], v[248:249], v[120:121]
	global_store_dwordx4 v74, v[120:123], s[98:99] nt
	s_add_u32 s98, s98, 0x8000
	s_addc_u32 s99, s99, 0
	s_waitcnt vmcnt(15) lgkmcnt(3)
	v_pk_fma_f32 v[126:127], v[2:3], v[146:147], v[126:127]
	v_pk_fma_f32 v[124:125], v[0:1], v[144:145], v[124:125]
	global_store_dwordx4 v74, v[124:127], s[98:99] nt
	s_add_u32 s98, s98, 0x8000
	s_addc_u32 s99, s99, 0
	s_waitcnt vmcnt(15) lgkmcnt(2)
	v_pk_fma_f32 v[130:131], v[2:3], v[150:151], v[130:131]
	v_pk_fma_f32 v[128:129], v[0:1], v[148:149], v[128:129]
	global_store_dwordx4 v74, v[128:131], s[98:99] nt
	s_add_u32 s98, s98, 0x8000
	s_addc_u32 s99, s99, 0
	s_waitcnt vmcnt(15) lgkmcnt(1)
	v_pk_fma_f32 v[134:135], v[2:3], v[154:155], v[134:135]
	v_pk_fma_f32 v[132:133], v[0:1], v[152:153], v[132:133]
	global_store_dwordx4 v74, v[132:135], s[98:99] nt
	s_add_u32 s98, s98, 0x8000
	s_addc_u32 s99, s99, 0
	s_waitcnt vmcnt(15) lgkmcnt(0)
	v_pk_fma_f32 v[138:139], v[2:3], v[158:159], v[138:139]
	v_pk_fma_f32 v[136:137], v[0:1], v[156:157], v[136:137]
	global_store_dwordx4 v74, v[136:139], s[98:99] nt
	s_and_b64 vcc, exec, s[0:1]
	s_mov_b32 s6, s13
	s_mov_b32 s14, s12
	s_barrier
	s_cbranch_vccz .LBB0_690
